# MLA out-proj GEMM (head-strided A, 192B K step) also moved to the LDS-DMA 16x16x32 pipeline
# speedup vs baseline: 1.1298x; 1.0021x over previous
; DI int otid() { int t = threadIdx.x; asm volatile("" : "+v"(t)); return t; }
; template <bool SWAP, bool HALF>
; DI void gemm_mainloop(const GemmDesc& d, int m0, int n0, bf16_t* smem, f32x16 (&acc)[2][2], int dry) {
;   const int t = otid(), lane = t & 63, w = t >> 6, wm = w >> 1, wn = w & 1, r = lane & 31, hh = lane >> 5;
;   const int lrow = t >> 3, lkc = t & 7;
;   const bf16_t* ap[4]; const bf16_t* bp[4];
; #pragma unroll
;   for (int i = 0; i < 4; ++i) {
;     int am = m0 + lrow + 32 * i; am = am < M ? am : M - 1;
;     ap[i] = d.A + (size_t)am * d.lda + lkc * 8 + (d.a_grp ? (n0 / d.a_grp) * d.a_grp : 0);
;     bp[i] = d.Bt + (size_t)(n0 + lrow + 32 * i) * d.ldb + lkc * 8;
;   }
; #pragma unroll
;   for (int a = 0; a < 2; ++a)
; #pragma unroll
;     for (int b = 0; b < 2; ++b)
; #pragma unroll
;       for (int i = 0; i < 16; ++i) acc[a][b][i] = 0.f;
;   u32x4 ra0[4], rb0[4], ra1[4], rb1[4];
;   const int nk = d.K >> 6;
;   const int lds_w = lrow * LST + lkc * 8;
;   auto gl = [&](u32x4 (&ra)[4], u32x4 (&rb)[4], int ks) {
; #pragma unroll
;     for (int i = 0; i < 4; ++i) {
;       ra[i] = *(const u32x4*)(ap[i] + (size_t)ks * d.a_cs);
;       __builtin_amdgcn_sched_barrier(0);
;       rb[i] = *(const u32x4*)(bp[i] + (size_t)ks * 64);
;       __builtin_amdgcn_sched_barrier(0);
;     }
;   };
;   const int nM = (M + 127) / 128, nN = d.N >> 7;
;   const int x = blockIdx.x & 7, slot = blockIdx.x >> 3, nslots = gridDim.x >> 3;
;   const int cx = (nM - x + 7) >> 3, total = cx * nN;
;   for (int i = slot; i < total; i += nslots) {
;     const int g = i / (8 * nN), j = i - g * 8 * nN;
;     const int gm = (cx - g * 8) < 8 ? (cx - g * 8) : 8;
;     const int mt = (g * 8 + j % gm) * 8 + x, nt = j / gm;
;     gemm_tile(d, mt * 128, nt * 128, smem, dry);
.LBB0_919:
	s_lshr_b32 s1, s8, 3
	s_and_b32 s1, s1, 0xffffff8
	v_readlane_b32 s5, v228, 38
	s_sub_i32 s5, s5, s1
	s_min_i32 s5, s5, 8
	s_abs_i32 s9, s5
	v_cvt_f32_u32_e32 v0, s9
	s_sub_i32 s10, 0, s9
	s_lshl_b32 s4, s1, 3
	s_sub_i32 s4, s8, s4
	v_rcp_iflag_f32_e32 v0, v0
	s_abs_i32 s7, s4
	s_xor_b32 s6, s4, s5
	s_ashr_i32 s6, s6, 31
	v_mul_f32_e32 v0, 0x4f7ffffe, v0
	v_cvt_u32_f32_e32 v0, v0
	v_mov_b32_e32 v150, v172
	v_mov_b32_e32 v32, v172
	v_readfirstlane_b32 s11, v0
	s_mul_i32 s10, s10, s11
	s_mul_hi_u32 s10, s11, s10
	s_add_i32 s11, s11, s10
	s_mul_hi_u32 s10, s7, s11
	s_mul_i32 s11, s10, s9
	s_sub_i32 s7, s7, s11
	s_add_i32 s11, s10, 1
	s_sub_i32 s12, s7, s9
	s_cmp_ge_u32 s7, s9
	s_cselect_b32 s10, s11, s10
	s_cselect_b32 s7, s12, s7
	s_add_i32 s11, s10, 1
	s_cmp_ge_u32 s7, s9
	s_cselect_b32 s7, s11, s10
	s_xor_b32 s7, s7, s6
	s_sub_i32 s6, s7, s6
	s_mul_i32 s5, s6, s5
	s_sub_i32 s4, s4, s5
	s_add_i32 s1, s1, s4
	s_lshl_b32 s1, s1, 10
	s_or_b32 s9, s1, s29
	v_lshlrev_b32_e32 v0, 3, v32
	v_ashrrev_i32_e32 v6, 3, v32
	v_and_b32_e32 v33, 56, v0
	s_lshl_b32 s4, s6, 7
	v_add_u32_e32 v7, s9, v6
	v_lshlrev_b32_e32 v144, 1, v33
	v_lshl_add_u64 v[0:1], s[68:69], 0, v[144:145]
	v_add_u32_e32 v2, s4, v6
	v_readlane_b32 s76, v228, 60
	v_min_i32_e32 v3, 0x803f, v7
	s_movk_i32 s1, 0xc00
	v_readlane_b32 s88, v223, 8
	v_readlane_b32 s89, v223, 9
	v_mad_i64_i32 v[152:153], s[6:7], v3, s1, v[0:1]
	v_ashrrev_i32_e32 v3, 31, v2
	v_lshl_add_u64 v[4:5], s[88:89], 0, v[144:145]
	v_lshlrev_b64 v[2:3], 11, v[2:3]
	v_lshl_add_u64 v[154:155], v[4:5], 0, v[2:3]
	v_min_i32_e32 v2, 0x801f, v7
	v_add_u32_e32 v2, 32, v2
	v_mad_i64_i32 v[156:157], s[6:7], v2, s1, v[0:1]
	v_min_i32_e32 v2, 0x7fff, v7
	s_mov_b64 s[6:7], 0x10000
	v_add_u32_e32 v2, 64, v2
	v_lshl_add_u64 v[158:159], v[154:155], 0, s[6:7]
	v_mad_i64_i32 v[160:161], s[6:7], v2, s1, v[0:1]
	v_min_i32_e32 v2, 0x7fdf, v7
	s_mov_b64 s[6:7], 0x20000
	v_add_u32_e32 v2, 0x60, v2
	v_lshl_add_u64 v[162:163], v[154:155], 0, s[6:7]
	v_mad_i64_i32 v[164:165], s[6:7], v2, s1, v[0:1]
	s_mov_b64 s[6:7], 0x30000
	s_movk_i32 s1, 0x48
	v_lshl_add_u64 v[166:167], v[154:155], 0, s[6:7]
	v_and_b32_e32 v34, 31, v32
	v_mul_lo_u32 v35, v6, s1
	v_readlane_b32 s77, v228, 61
	v_readlane_b32 s78, v228, 62
	v_readlane_b32 s79, v228, 63
	v_readlane_b32 s80, v223, 0
	v_readlane_b32 s81, v223, 1
	v_readlane_b32 s82, v223, 2
	v_readlane_b32 s83, v223, 3
	v_readlane_b32 s84, v223, 4
	v_readlane_b32 s85, v223, 5
	v_readlane_b32 s86, v223, 6
	v_readlane_b32 s87, v223, 7
	v_readlane_b32 s90, v223, 10
	v_readlane_b32 s91, v223, 11
	s_mov_b32 s1, 0x10000
	s_waitcnt vmcnt(19)
	v_add_co_u32_e32 v12, vcc, s1, v154
	s_nop 1
	v_addc_co_u32_e32 v13, vcc, 0, v155, vcc
	s_nop 0
	s_mov_b32 s1, 0x20000
	v_add_co_u32_e32 v20, vcc, s1, v154
	s_nop 1
	v_addc_co_u32_e32 v21, vcc, 0, v155, vcc
	s_nop 0
	s_mov_b32 s1, 0x30000
	v_add_co_u32_e32 v28, vcc, s1, v154
	s_nop 1
	v_addc_co_u32_e32 v29, vcc, 0, v155, vcc
	s_nop 0
	v_add_lshl_u32 v144, v35, v33, 1
	s_waitcnt vmcnt(15)
	s_waitcnt vmcnt(14)
	s_waitcnt vmcnt(13)
	s_waitcnt vmcnt(12)
	s_waitcnt vmcnt(11)
	s_waitcnt vmcnt(10)
	s_waitcnt vmcnt(9)
	s_waitcnt vmcnt(8)
	v_lshrrev_b32_e32 v0, 1, v32
	v_and_or_b32 v1, v0, s72, v34
	v_and_b32_e32 v0, 16, v0
	s_movk_i32 s1, 0x90
	v_mad_u64_u32 v[168:169], s[6:7], v1, s1, v[0:1]
	v_and_b32_e32 v1, 0x5f, v32
	v_mul_u32_u24_e32 v1, 0x48, v1
	v_lshl_add_u32 v169, v1, 1, v0
	v_bfe_u32 v212, v172, 4, 3
	v_lshlrev_b32_e32 v212, 4, v212
	v_and_b32_e32 v213, 7, v172
	v_lshlrev_b32_e32 v213, 4, v213
	v_xor_b32_e32 v214, v213, v212
	v_sub_u32_e32 v210, v214, v213
	v_ashrrev_i32_e32 v211, 31, v210
	v_lshl_add_u64 v[152:153], v[152:153], 0, v[210:211]
	v_xor_b32_e32 v154, v154, v212
	v_lshl_add_u64 v[156:157], v[156:157], 0, v[210:211]
	v_xor_b32_e32 v158, v158, v212
	v_lshl_add_u64 v[160:161], v[160:161], 0, v[210:211]
	v_xor_b32_e32 v162, v162, v212
	v_lshl_add_u64 v[164:165], v[164:165], 0, v[210:211]
	v_xor_b32_e32 v166, v166, v212
	v_lshrrev_b32_e32 v213, 6, v172
	s_nop 1
	v_readfirstlane_b32 s101, v213
	s_lshl_b32 s101, s101, 10
	s_add_u32 m0, s101, 0x0
	s_nop 0
	global_load_lds_dwordx4 v[152:153], off
	s_add_u32 m0, s101, 0x4000
	s_nop 0
	global_load_lds_dwordx4 v[154:155], off
	s_add_u32 m0, s101, 0x1000
	s_nop 0
	global_load_lds_dwordx4 v[156:157], off
	s_add_u32 m0, s101, 0x5000
	s_nop 0
	global_load_lds_dwordx4 v[158:159], off
	s_add_u32 m0, s101, 0x2000
	s_nop 0
	global_load_lds_dwordx4 v[160:161], off
	s_add_u32 m0, s101, 0x6000
	s_nop 0
	global_load_lds_dwordx4 v[162:163], off
	s_add_u32 m0, s101, 0x3000
	s_nop 0
	global_load_lds_dwordx4 v[164:165], off
	s_add_u32 m0, s101, 0x7000
	s_nop 0
	global_load_lds_dwordx4 v[166:167], off
	v_and_b32_e32 v212, 15, v172
	v_bfe_u32 v213, v172, 4, 2
	v_lshrrev_b32_e32 v214, 1, v212
	v_xor_b32_e32 v213, v213, v214
	v_lshlrev_b32_e32 v213, 4, v213
	v_lshl_or_b32 v212, v212, 7, v213
	v_lshrrev_b32_e32 v214, 7, v172
	v_lshl_add_u32 v168, v214, 13, v212
	v_bfe_u32 v214, v172, 6, 1
	v_lshl_add_u32 v169, v214, 13, v212
	v_add_u32_e32 v169, 0x4000, v169
	v_xor_b32_e32 v220, 64, v168
	v_xor_b32_e32 v221, 64, v169
	s_waitcnt vmcnt(0)
	s_waitcnt lgkmcnt(0)
	s_barrier
; template <bool SWAP, bool HALF>
; DI void gemm_mainloop(const GemmDesc& d, int m0, int n0, bf16_t* smem, f32x16 (&acc)[2][2], int dry) {
;     ...
; #pragma unroll
;   for (int a = 0; a < 2; ++a)
; #pragma unroll
;     for (int b = 0; b < 2; ++b)
; #pragma unroll
;       for (int i = 0; i < 16; ++i) acc[a][b][i] = 0.f;
;   u32x4 ra0[4], rb0[4], ra1[4], rb1[4];
;   const int nk = d.K >> 6;
;   const int lds_w = lrow * LST + lkc * 8;
;   auto gl = [&](u32x4 (&ra)[4], u32x4 (&rb)[4], int ks) {
; #pragma unroll
;     for (int i = 0; i < 4; ++i) {
;       ra[i] = *(const u32x4*)(ap[i] + (size_t)ks * d.a_cs);
;       __builtin_amdgcn_sched_barrier(0);
;       rb[i] = *(const u32x4*)(bp[i] + (size_t)ks * 64);
;       __builtin_amdgcn_sched_barrier(0);
;     }
;   };
;   auto lw = [&](const u32x4 (&ra)[4], const u32x4 (&rb)[4], int buf) {
;     bf16_t* An = smem + buf * 2 * TILE_EL + lds_w; bf16_t* Bn = An + TILE_EL;
; #pragma unroll
;     for (int i = 0; i < 4; ++i) {
;       *(u32x4*)(An + 32 * i * LST) = ra[i];
;       *(u32x4*)(Bn + 32 * i * LST) = rb[i];
;     }
;   };
;   bf16x8 fa[2][2], fb[2][2];
;   auto ldf = [&](int buf, int kk, int set) {
;     const bf16_t* Ab = smem + buf * 2 * TILE_EL + ((HALF ? 0 : wm * 64) + r) * LST + 8 * hh + kk * 16;
;     const bf16_t* Bb = smem + buf * 2 * TILE_EL + TILE_EL + ((HALF ? w * 32 : wn * 64) + r) * LST + 8 * hh + kk * 16;
; #pragma unroll
;     for (int i = 0; i < 2; ++i) { fa[set][i] = *(const bf16x8*)(Ab + i * 32 * LST); if (!HALF || i == 0) fb[set][i] = *(const bf16x8*)(Bb + i * 32 * LST); }
;   };
;   auto mma = [&](int set) {
; #pragma unroll
;     for (int a = 0; a < 2; ++a)
; #pragma unroll
;       for (int b = 0; b < (HALF ? 1 : 2); ++b) {
;         if (SWAP) acc[a][b] = MFMA32(fb[set][b], fa[set][a], acc[a][b]);
;         else      acc[a][b] = MFMA32(fa[set][a], fb[set][b], acc[a][b]);
;       }
;   };
;     ...
;   auto stage = [&](int cur, u32x4 (&ran)[4], u32x4 (&rbn)[4], int ks) {
;     ldf(cur, 1, 1); SB_;
;     mma(0); SB_;
;     ldf(cur, 2, 0); SB_;
;     lw(ran, rbn, cur ^ 1);
;     gl(ran, rbn, (ks + 3 < nk) ? ks + 3 : nk - 1);
;     SB_;
;     mma(1); SB_;
;     __syncthreads();
;     ldf(cur, 3, 1); SB_;
;     mma(0); SB_;
;     ldf(cur ^ 1, 0, 0);
;     SB_;
;     mma(1); SB_;
;     __syncthreads();
;   };
;   gl(ra0, rb0, 0);
;   gl(ra1, rb1, 1);
;   lw(ra0, rb0, 0);
;   gl(ra0, rb0, 2);
;   __syncthreads();
	v_mov_b32_e32 v0, 0
	v_add_u32_e32 v170, 0x9000, v144
	s_mov_b32 s1, -2
	v_mov_b32_e32 v1, v0
	v_mov_b32_e32 v2, v0
	v_mov_b32_e32 v3, v0
	v_mov_b32_e32 v4, v0
	v_mov_b32_e32 v5, v0
	v_mov_b32_e32 v6, v0
	v_mov_b32_e32 v7, v0
	v_mov_b32_e32 v8, v0
	v_mov_b32_e32 v9, v0
	v_mov_b32_e32 v10, v0
	v_mov_b32_e32 v11, v0
	v_mov_b32_e32 v12, v0
	v_mov_b32_e32 v13, v0
	v_mov_b32_e32 v14, v0
	v_mov_b32_e32 v15, v0
	v_mov_b32_e32 v16, v0
	v_mov_b32_e32 v17, v0
	v_mov_b32_e32 v18, v0
	v_mov_b32_e32 v19, v0
	v_mov_b32_e32 v20, v0
	v_mov_b32_e32 v21, v0
	v_mov_b32_e32 v22, v0
	v_mov_b32_e32 v23, v0
	v_mov_b32_e32 v24, v0
	v_mov_b32_e32 v25, v0
	v_mov_b32_e32 v26, v0
	v_mov_b32_e32 v27, v0
	v_mov_b32_e32 v28, v0
	v_mov_b32_e32 v29, v0
	v_mov_b32_e32 v30, v0
	v_mov_b32_e32 v31, v0
	v_mov_b32_e32 v32, v0
	v_mov_b32_e32 v33, v0
	v_mov_b32_e32 v34, v0
	v_mov_b32_e32 v35, v0
	v_mov_b32_e32 v36, v0
	v_mov_b32_e32 v37, v0
	v_mov_b32_e32 v38, v0
	v_mov_b32_e32 v39, v0
	v_mov_b32_e32 v40, v0
	v_mov_b32_e32 v41, v0
	v_mov_b32_e32 v42, v0
	v_mov_b32_e32 v43, v0
	v_mov_b32_e32 v44, v0
	v_mov_b32_e32 v45, v0
	v_mov_b32_e32 v46, v0
	v_mov_b32_e32 v47, v0
	v_mov_b32_e32 v48, v0
	v_mov_b32_e32 v49, v0
	v_mov_b32_e32 v50, v0
	v_mov_b32_e32 v51, v0
	v_mov_b32_e32 v52, v0
	v_mov_b32_e32 v53, v0
	v_mov_b32_e32 v54, v0
	v_mov_b32_e32 v55, v0
	v_mov_b32_e32 v56, v0
	v_mov_b32_e32 v57, v0
	v_mov_b32_e32 v58, v0
	v_mov_b32_e32 v59, v0
	v_mov_b32_e32 v60, v0
	v_mov_b32_e32 v61, v0
	v_mov_b32_e32 v62, v0
	v_mov_b32_e32 v63, v0
	ds_read_b128 v[64:67], v168 offset:0
	ds_read_b128 v[68:71], v168 offset:2048
	ds_read_b128 v[72:75], v168 offset:4096
	ds_read_b128 v[76:79], v168 offset:6144
	ds_read_b128 v[80:83], v169 offset:0
	ds_read_b128 v[84:87], v169 offset:2048
	ds_read_b128 v[88:91], v169 offset:4096
	ds_read_b128 v[92:95], v169 offset:6144
	s_add_i32 s5, s1, 3
	s_min_u32 s5, s5, 15
	s_lshl_b32 s18, s5, 7
	s_mul_i32 s6, s5, 0xc0
	s_mov_b32 s7, s19
	s_add_u32 m0, s101, 0x8000
	v_lshl_add_u64 v[210:211], v[152:153], 0, s[6:7]
	global_load_lds_dwordx4 v[210:211], off
	s_add_u32 m0, s101, 0xc000
	v_lshl_add_u64 v[210:211], v[154:155], 0, s[18:19]
	global_load_lds_dwordx4 v[210:211], off
	ds_read_b128 v[96:99], v220 offset:0
	ds_read_b128 v[100:103], v220 offset:2048
	ds_read_b128 v[104:107], v220 offset:4096
	ds_read_b128 v[108:111], v220 offset:6144
	ds_read_b128 v[112:115], v221 offset:0
	ds_read_b128 v[116:119], v221 offset:2048
	ds_read_b128 v[120:123], v221 offset:4096
	ds_read_b128 v[124:127], v221 offset:6144
	s_waitcnt lgkmcnt(8)
	v_mfma_f32_16x16x32_bf16 v[0:3], v[80:83], v[64:67], v[0:3]
	v_mfma_f32_16x16x32_bf16 v[4:7], v[84:87], v[64:67], v[4:7]
	s_add_u32 m0, s101, 0x9000
	v_lshl_add_u64 v[210:211], v[156:157], 0, s[6:7]
	global_load_lds_dwordx4 v[210:211], off
	v_mfma_f32_16x16x32_bf16 v[8:11], v[88:91], v[64:67], v[8:11]
	v_mfma_f32_16x16x32_bf16 v[12:15], v[92:95], v[64:67], v[12:15]
	s_add_u32 m0, s101, 0xd000
	v_lshl_add_u64 v[210:211], v[158:159], 0, s[18:19]
	global_load_lds_dwordx4 v[210:211], off
	v_mfma_f32_16x16x32_bf16 v[16:19], v[80:83], v[68:71], v[16:19]
	v_mfma_f32_16x16x32_bf16 v[20:23], v[84:87], v[68:71], v[20:23]
	s_add_u32 m0, s101, 0xa000
	v_lshl_add_u64 v[210:211], v[160:161], 0, s[6:7]
	global_load_lds_dwordx4 v[210:211], off
	v_mfma_f32_16x16x32_bf16 v[24:27], v[88:91], v[68:71], v[24:27]
	v_mfma_f32_16x16x32_bf16 v[28:31], v[92:95], v[68:71], v[28:31]
	s_add_u32 m0, s101, 0xe000
	v_lshl_add_u64 v[210:211], v[162:163], 0, s[18:19]
	global_load_lds_dwordx4 v[210:211], off
	v_mfma_f32_16x16x32_bf16 v[32:35], v[80:83], v[72:75], v[32:35]
	v_mfma_f32_16x16x32_bf16 v[36:39], v[84:87], v[72:75], v[36:39]
	s_add_u32 m0, s101, 0xb000
	v_lshl_add_u64 v[210:211], v[164:165], 0, s[6:7]
	global_load_lds_dwordx4 v[210:211], off
	v_mfma_f32_16x16x32_bf16 v[40:43], v[88:91], v[72:75], v[40:43]
	v_mfma_f32_16x16x32_bf16 v[44:47], v[92:95], v[72:75], v[44:47]
	s_add_u32 m0, s101, 0xf000
	v_lshl_add_u64 v[210:211], v[166:167], 0, s[18:19]
	global_load_lds_dwordx4 v[210:211], off
	v_mfma_f32_16x16x32_bf16 v[48:51], v[80:83], v[76:79], v[48:51]
	v_mfma_f32_16x16x32_bf16 v[52:55], v[84:87], v[76:79], v[52:55]
	v_mfma_f32_16x16x32_bf16 v[56:59], v[88:91], v[76:79], v[56:59]
	v_mfma_f32_16x16x32_bf16 v[60:63], v[92:95], v[76:79], v[60:63]
	s_waitcnt vmcnt(0)
	s_waitcnt lgkmcnt(0)
	s_barrier
; #define MFMA32(a, b, c) __builtin_amdgcn_mfma_f32_32x32x16_bf16((a), (b), (c), 0, 0, 0)
; #define SB_ __builtin_amdgcn_sched_barrier(0)
; template <bool SWAP, bool HALF>
; DI void gemm_mainloop(const GemmDesc& d, int m0, int n0, bf16_t* smem, f32x16 (&acc)[2][2], int dry) {
;     ...
;   auto ldf = [&](int buf, int kk, int set) {
;     const bf16_t* Ab = smem + buf * 2 * TILE_EL + ((HALF ? 0 : wm * 64) + r) * LST + 8 * hh + kk * 16;
;     const bf16_t* Bb = smem + buf * 2 * TILE_EL + TILE_EL + ((HALF ? w * 32 : wn * 64) + r) * LST + 8 * hh + kk * 16;
; #pragma unroll
;     for (int i = 0; i < 2; ++i) { fa[set][i] = *(const bf16x8*)(Ab + i * 32 * LST); if (!HALF || i == 0) fb[set][i] = *(const bf16x8*)(Bb + i * 32 * LST); }
;   };
;   auto mma = [&](int set) {
; #pragma unroll
;     for (int a = 0; a < 2; ++a)
; #pragma unroll
;       for (int b = 0; b < (HALF ? 1 : 2); ++b) {
;         if (SWAP) acc[a][b] = MFMA32(fb[set][b], fa[set][a], acc[a][b]);
;         else      acc[a][b] = MFMA32(fa[set][a], fb[set][b], acc[a][b]);
;       }
;   };
;     ...
;   auto stage = [&](int cur, u32x4 (&ran)[4], u32x4 (&rbn)[4], int ks) {
;     ldf(cur, 1, 1); SB_;
;     mma(0); SB_;
;     ldf(cur, 2, 0); SB_;
;     lw(ran, rbn, cur ^ 1);
;     gl(ran, rbn, (ks + 3 < nk) ? ks + 3 : nk - 1);
;     SB_;
;     mma(1); SB_;
;     __syncthreads();
;     ldf(cur, 3, 1); SB_;
;     mma(0); SB_;
;     ldf(cur ^ 1, 0, 0);
;     SB_;
;     mma(1); SB_;
;     __syncthreads();
;   };
;   gl(ra0, rb0, 0);
;   gl(ra1, rb1, 1);
;   lw(ra0, rb0, 0);
;   gl(ra0, rb0, 2);
;   __syncthreads();
;   ldf(0, 0, 0);
; #pragma unroll 1
;   for (int ks = 0; ks < nk; ks += 2) {
;     stage(0, ra1, rb1, ks);
;     stage(1, ra0, rb0, ks + 1);
;   }
.LBB0_920:
	ds_read_b128 v[64:67], v168 offset:32768
	ds_read_b128 v[68:71], v168 offset:34816
	ds_read_b128 v[72:75], v168 offset:36864
	ds_read_b128 v[76:79], v168 offset:38912
	ds_read_b128 v[80:83], v169 offset:32768
	ds_read_b128 v[84:87], v169 offset:34816
	ds_read_b128 v[88:91], v169 offset:36864
	ds_read_b128 v[92:95], v169 offset:38912
	s_add_i32 s1, s1, 2
	s_add_i32 s5, s1, 2
	s_min_u32 s5, s5, 15
	s_lshl_b32 s18, s5, 7
	s_mul_i32 s6, s5, 0xc0
	s_mov_b32 s7, s19
	s_add_u32 m0, s101, 0x0
	v_lshl_add_u64 v[210:211], v[152:153], 0, s[6:7]
	global_load_lds_dwordx4 v[210:211], off
	s_add_u32 m0, s101, 0x4000
	v_lshl_add_u64 v[210:211], v[154:155], 0, s[18:19]
	global_load_lds_dwordx4 v[210:211], off
	ds_read_b128 v[128:131], v220 offset:32768
	ds_read_b128 v[132:135], v220 offset:34816
	ds_read_b128 v[136:139], v220 offset:36864
	ds_read_b128 v[140:143], v220 offset:38912
	ds_read_b128 v[192:195], v221 offset:32768
	ds_read_b128 v[196:199], v221 offset:34816
	ds_read_b128 v[200:203], v221 offset:36864
	ds_read_b128 v[204:207], v221 offset:38912
	v_mfma_f32_16x16x32_bf16 v[0:3], v[112:115], v[96:99], v[0:3]
	v_mfma_f32_16x16x32_bf16 v[4:7], v[116:119], v[96:99], v[4:7]
	s_add_u32 m0, s101, 0x1000
	v_lshl_add_u64 v[210:211], v[156:157], 0, s[6:7]
	global_load_lds_dwordx4 v[210:211], off
	v_mfma_f32_16x16x32_bf16 v[8:11], v[120:123], v[96:99], v[8:11]
	v_mfma_f32_16x16x32_bf16 v[12:15], v[124:127], v[96:99], v[12:15]
	s_add_u32 m0, s101, 0x5000
	v_lshl_add_u64 v[210:211], v[158:159], 0, s[18:19]
	global_load_lds_dwordx4 v[210:211], off
	v_mfma_f32_16x16x32_bf16 v[16:19], v[112:115], v[100:103], v[16:19]
	v_mfma_f32_16x16x32_bf16 v[20:23], v[116:119], v[100:103], v[20:23]
	s_add_u32 m0, s101, 0x2000
	v_lshl_add_u64 v[210:211], v[160:161], 0, s[6:7]
	global_load_lds_dwordx4 v[210:211], off
	v_mfma_f32_16x16x32_bf16 v[24:27], v[120:123], v[100:103], v[24:27]
	v_mfma_f32_16x16x32_bf16 v[28:31], v[124:127], v[100:103], v[28:31]
	s_add_u32 m0, s101, 0x6000
	v_lshl_add_u64 v[210:211], v[162:163], 0, s[18:19]
	global_load_lds_dwordx4 v[210:211], off
	v_mfma_f32_16x16x32_bf16 v[32:35], v[112:115], v[104:107], v[32:35]
	v_mfma_f32_16x16x32_bf16 v[36:39], v[116:119], v[104:107], v[36:39]
	s_add_u32 m0, s101, 0x3000
	v_lshl_add_u64 v[210:211], v[164:165], 0, s[6:7]
	global_load_lds_dwordx4 v[210:211], off
	v_mfma_f32_16x16x32_bf16 v[40:43], v[120:123], v[104:107], v[40:43]
	v_mfma_f32_16x16x32_bf16 v[44:47], v[124:127], v[104:107], v[44:47]
	s_add_u32 m0, s101, 0x7000
	v_lshl_add_u64 v[210:211], v[166:167], 0, s[18:19]
	global_load_lds_dwordx4 v[210:211], off
	v_mfma_f32_16x16x32_bf16 v[48:51], v[112:115], v[108:111], v[48:51]
	v_mfma_f32_16x16x32_bf16 v[52:55], v[116:119], v[108:111], v[52:55]
	v_mfma_f32_16x16x32_bf16 v[56:59], v[120:123], v[108:111], v[56:59]
	v_mfma_f32_16x16x32_bf16 v[60:63], v[124:127], v[108:111], v[60:63]
	s_waitcnt lgkmcnt(8)
	v_mfma_f32_16x16x32_bf16 v[0:3], v[80:83], v[64:67], v[0:3]
	v_mfma_f32_16x16x32_bf16 v[4:7], v[84:87], v[64:67], v[4:7]
	v_mfma_f32_16x16x32_bf16 v[8:11], v[88:91], v[64:67], v[8:11]
	v_mfma_f32_16x16x32_bf16 v[12:15], v[92:95], v[64:67], v[12:15]
	v_mfma_f32_16x16x32_bf16 v[16:19], v[80:83], v[68:71], v[16:19]
	v_mfma_f32_16x16x32_bf16 v[20:23], v[84:87], v[68:71], v[20:23]
	v_mfma_f32_16x16x32_bf16 v[24:27], v[88:91], v[68:71], v[24:27]
	v_mfma_f32_16x16x32_bf16 v[28:31], v[92:95], v[68:71], v[28:31]
	v_mfma_f32_16x16x32_bf16 v[32:35], v[80:83], v[72:75], v[32:35]
	v_mfma_f32_16x16x32_bf16 v[36:39], v[84:87], v[72:75], v[36:39]
	v_mfma_f32_16x16x32_bf16 v[40:43], v[88:91], v[72:75], v[40:43]
	v_mfma_f32_16x16x32_bf16 v[44:47], v[92:95], v[72:75], v[44:47]
	v_mfma_f32_16x16x32_bf16 v[48:51], v[80:83], v[76:79], v[48:51]
	v_mfma_f32_16x16x32_bf16 v[52:55], v[84:87], v[76:79], v[52:55]
	v_mfma_f32_16x16x32_bf16 v[56:59], v[88:91], v[76:79], v[56:59]
	v_mfma_f32_16x16x32_bf16 v[60:63], v[92:95], v[76:79], v[60:63]
	s_waitcnt vmcnt(0)
	s_waitcnt lgkmcnt(0)
	s_barrier
	ds_read_b128 v[64:67], v168 offset:0
	ds_read_b128 v[68:71], v168 offset:2048
	ds_read_b128 v[72:75], v168 offset:4096
	ds_read_b128 v[76:79], v168 offset:6144
	ds_read_b128 v[80:83], v169 offset:0
	ds_read_b128 v[84:87], v169 offset:2048
	ds_read_b128 v[88:91], v169 offset:4096
	ds_read_b128 v[92:95], v169 offset:6144
	s_add_i32 s5, s1, 3
	s_min_u32 s5, s5, 15
	s_lshl_b32 s18, s5, 7
	s_mul_i32 s6, s5, 0xc0
	s_mov_b32 s7, s19
	s_add_u32 m0, s101, 0x8000
	v_lshl_add_u64 v[210:211], v[152:153], 0, s[6:7]
	global_load_lds_dwordx4 v[210:211], off
	s_add_u32 m0, s101, 0xc000
	v_lshl_add_u64 v[210:211], v[154:155], 0, s[18:19]
	global_load_lds_dwordx4 v[210:211], off
	ds_read_b128 v[96:99], v220 offset:0
	ds_read_b128 v[100:103], v220 offset:2048
	ds_read_b128 v[104:107], v220 offset:4096
	ds_read_b128 v[108:111], v220 offset:6144
	ds_read_b128 v[112:115], v221 offset:0
	ds_read_b128 v[116:119], v221 offset:2048
	ds_read_b128 v[120:123], v221 offset:4096
	ds_read_b128 v[124:127], v221 offset:6144
	v_mfma_f32_16x16x32_bf16 v[0:3], v[192:195], v[128:131], v[0:3]
	v_mfma_f32_16x16x32_bf16 v[4:7], v[196:199], v[128:131], v[4:7]
	s_add_u32 m0, s101, 0x9000
	v_lshl_add_u64 v[210:211], v[156:157], 0, s[6:7]
	global_load_lds_dwordx4 v[210:211], off
	v_mfma_f32_16x16x32_bf16 v[8:11], v[200:203], v[128:131], v[8:11]
	v_mfma_f32_16x16x32_bf16 v[12:15], v[204:207], v[128:131], v[12:15]
	s_add_u32 m0, s101, 0xd000
	v_lshl_add_u64 v[210:211], v[158:159], 0, s[18:19]
	global_load_lds_dwordx4 v[210:211], off
	v_mfma_f32_16x16x32_bf16 v[16:19], v[192:195], v[132:135], v[16:19]
	v_mfma_f32_16x16x32_bf16 v[20:23], v[196:199], v[132:135], v[20:23]
	s_add_u32 m0, s101, 0xa000
	v_lshl_add_u64 v[210:211], v[160:161], 0, s[6:7]
	global_load_lds_dwordx4 v[210:211], off
	v_mfma_f32_16x16x32_bf16 v[24:27], v[200:203], v[132:135], v[24:27]
	v_mfma_f32_16x16x32_bf16 v[28:31], v[204:207], v[132:135], v[28:31]
	s_add_u32 m0, s101, 0xe000
	v_lshl_add_u64 v[210:211], v[162:163], 0, s[18:19]
	global_load_lds_dwordx4 v[210:211], off
	v_mfma_f32_16x16x32_bf16 v[32:35], v[192:195], v[136:139], v[32:35]
	v_mfma_f32_16x16x32_bf16 v[36:39], v[196:199], v[136:139], v[36:39]
	s_add_u32 m0, s101, 0xb000
	v_lshl_add_u64 v[210:211], v[164:165], 0, s[6:7]
	global_load_lds_dwordx4 v[210:211], off
	v_mfma_f32_16x16x32_bf16 v[40:43], v[200:203], v[136:139], v[40:43]
	v_mfma_f32_16x16x32_bf16 v[44:47], v[204:207], v[136:139], v[44:47]
	s_add_u32 m0, s101, 0xf000
	v_lshl_add_u64 v[210:211], v[166:167], 0, s[18:19]
	global_load_lds_dwordx4 v[210:211], off
	v_mfma_f32_16x16x32_bf16 v[48:51], v[192:195], v[140:143], v[48:51]
	v_mfma_f32_16x16x32_bf16 v[52:55], v[196:199], v[140:143], v[52:55]
	v_mfma_f32_16x16x32_bf16 v[56:59], v[200:203], v[140:143], v[56:59]
	v_mfma_f32_16x16x32_bf16 v[60:63], v[204:207], v[140:143], v[60:63]
	s_waitcnt lgkmcnt(8)
; #define MFMA32(a, b, c) __builtin_amdgcn_mfma_f32_32x32x16_bf16((a), (b), (c), 0, 0, 0)
; #define SB_ __builtin_amdgcn_sched_barrier(0)
; template <bool SWAP, bool HALF>
; DI void gemm_mainloop(const GemmDesc& d, int m0, int n0, bf16_t* smem, f32x16 (&acc)[2][2], int dry) {
;     ...
;   auto ldf = [&](int buf, int kk, int set) {
;     const bf16_t* Ab = smem + buf * 2 * TILE_EL + ((HALF ? 0 : wm * 64) + r) * LST + 8 * hh + kk * 16;
;     const bf16_t* Bb = smem + buf * 2 * TILE_EL + TILE_EL + ((HALF ? w * 32 : wn * 64) + r) * LST + 8 * hh + kk * 16;
; #pragma unroll
;     for (int i = 0; i < 2; ++i) { fa[set][i] = *(const bf16x8*)(Ab + i * 32 * LST); if (!HALF || i == 0) fb[set][i] = *(const bf16x8*)(Bb + i * 32 * LST); }
;   };
;   auto mma = [&](int set) {
; #pragma unroll
;     for (int a = 0; a < 2; ++a)
; #pragma unroll
;       for (int b = 0; b < (HALF ? 1 : 2); ++b) {
;         if (SWAP) acc[a][b] = MFMA32(fb[set][b], fa[set][a], acc[a][b]);
;         else      acc[a][b] = MFMA32(fa[set][a], fb[set][b], acc[a][b]);
;       }
;   };
;     ...
;   auto stage = [&](int cur, u32x4 (&ran)[4], u32x4 (&rbn)[4], int ks) {
;     ldf(cur, 1, 1); SB_;
;     mma(0); SB_;
;     ldf(cur, 2, 0); SB_;
;     lw(ran, rbn, cur ^ 1);
;     gl(ran, rbn, (ks + 3 < nk) ? ks + 3 : nk - 1);
;     SB_;
;     mma(1); SB_;
;     __syncthreads();
;     ldf(cur, 3, 1); SB_;
;     mma(0); SB_;
;     ldf(cur ^ 1, 0, 0);
;     SB_;
;     mma(1); SB_;
;     __syncthreads();
;   };
;   gl(ra0, rb0, 0);
;   gl(ra1, rb1, 1);
;   lw(ra0, rb0, 0);
;   gl(ra0, rb0, 2);
;   __syncthreads();
;   ldf(0, 0, 0);
; #pragma unroll 1
;   for (int ks = 0; ks < nk; ks += 2) {
;     stage(0, ra1, rb1, ks);
;     stage(1, ra0, rb0, ks + 1);
;   }
	v_mfma_f32_16x16x32_bf16 v[0:3], v[80:83], v[64:67], v[0:3]
	v_mfma_f32_16x16x32_bf16 v[4:7], v[84:87], v[64:67], v[4:7]
	v_mfma_f32_16x16x32_bf16 v[8:11], v[88:91], v[64:67], v[8:11]
	v_mfma_f32_16x16x32_bf16 v[12:15], v[92:95], v[64:67], v[12:15]
	v_mfma_f32_16x16x32_bf16 v[16:19], v[80:83], v[68:71], v[16:19]
	v_mfma_f32_16x16x32_bf16 v[20:23], v[84:87], v[68:71], v[20:23]
	v_mfma_f32_16x16x32_bf16 v[24:27], v[88:91], v[68:71], v[24:27]
	v_mfma_f32_16x16x32_bf16 v[28:31], v[92:95], v[68:71], v[28:31]
	v_mfma_f32_16x16x32_bf16 v[32:35], v[80:83], v[72:75], v[32:35]
	v_mfma_f32_16x16x32_bf16 v[36:39], v[84:87], v[72:75], v[36:39]
	v_mfma_f32_16x16x32_bf16 v[40:43], v[88:91], v[72:75], v[40:43]
	v_mfma_f32_16x16x32_bf16 v[44:47], v[92:95], v[72:75], v[44:47]
	v_mfma_f32_16x16x32_bf16 v[48:51], v[80:83], v[76:79], v[48:51]
	v_mfma_f32_16x16x32_bf16 v[52:55], v[84:87], v[76:79], v[52:55]
	v_mfma_f32_16x16x32_bf16 v[56:59], v[88:91], v[76:79], v[56:59]
	v_mfma_f32_16x16x32_bf16 v[60:63], v[92:95], v[76:79], v[60:63]
	s_cmp_lt_u32 s1, 12
	s_waitcnt vmcnt(0)
	s_waitcnt lgkmcnt(0)
	s_barrier
	s_cbranch_scc1 .LBB0_920
	ds_read_b128 v[64:67], v168 offset:32768
	ds_read_b128 v[68:71], v168 offset:34816
	ds_read_b128 v[72:75], v168 offset:36864
	ds_read_b128 v[76:79], v168 offset:38912
	ds_read_b128 v[80:83], v169 offset:32768
	ds_read_b128 v[84:87], v169 offset:34816
	ds_read_b128 v[88:91], v169 offset:36864
	ds_read_b128 v[92:95], v169 offset:38912
	ds_read_b128 v[128:131], v220 offset:32768
	ds_read_b128 v[132:135], v220 offset:34816
	ds_read_b128 v[136:139], v220 offset:36864
	ds_read_b128 v[140:143], v220 offset:38912
	ds_read_b128 v[192:195], v221 offset:32768
	ds_read_b128 v[196:199], v221 offset:34816
	ds_read_b128 v[200:203], v221 offset:36864
	ds_read_b128 v[204:207], v221 offset:38912
	v_mfma_f32_16x16x32_bf16 v[0:3], v[112:115], v[96:99], v[0:3]
	v_mfma_f32_16x16x32_bf16 v[4:7], v[116:119], v[96:99], v[4:7]
	v_mfma_f32_16x16x32_bf16 v[8:11], v[120:123], v[96:99], v[8:11]
	v_mfma_f32_16x16x32_bf16 v[12:15], v[124:127], v[96:99], v[12:15]
	v_mfma_f32_16x16x32_bf16 v[16:19], v[112:115], v[100:103], v[16:19]
	v_mfma_f32_16x16x32_bf16 v[20:23], v[116:119], v[100:103], v[20:23]
	v_mfma_f32_16x16x32_bf16 v[24:27], v[120:123], v[100:103], v[24:27]
	v_mfma_f32_16x16x32_bf16 v[28:31], v[124:127], v[100:103], v[28:31]
	v_mfma_f32_16x16x32_bf16 v[32:35], v[112:115], v[104:107], v[32:35]
	v_mfma_f32_16x16x32_bf16 v[36:39], v[116:119], v[104:107], v[36:39]
	v_mfma_f32_16x16x32_bf16 v[40:43], v[120:123], v[104:107], v[40:43]
	v_mfma_f32_16x16x32_bf16 v[44:47], v[124:127], v[104:107], v[44:47]
	v_mfma_f32_16x16x32_bf16 v[48:51], v[112:115], v[108:111], v[48:51]
	v_mfma_f32_16x16x32_bf16 v[52:55], v[116:119], v[108:111], v[52:55]
	v_mfma_f32_16x16x32_bf16 v[56:59], v[120:123], v[108:111], v[56:59]
	v_mfma_f32_16x16x32_bf16 v[60:63], v[124:127], v[108:111], v[60:63]
	s_waitcnt lgkmcnt(8)
	v_mfma_f32_16x16x32_bf16 v[0:3], v[80:83], v[64:67], v[0:3]
	v_mfma_f32_16x16x32_bf16 v[4:7], v[84:87], v[64:67], v[4:7]
	v_mfma_f32_16x16x32_bf16 v[8:11], v[88:91], v[64:67], v[8:11]
	v_mfma_f32_16x16x32_bf16 v[12:15], v[92:95], v[64:67], v[12:15]
	v_mfma_f32_16x16x32_bf16 v[16:19], v[80:83], v[68:71], v[16:19]
	v_mfma_f32_16x16x32_bf16 v[20:23], v[84:87], v[68:71], v[20:23]
	v_mfma_f32_16x16x32_bf16 v[24:27], v[88:91], v[68:71], v[24:27]
	v_mfma_f32_16x16x32_bf16 v[28:31], v[92:95], v[68:71], v[28:31]
	v_mfma_f32_16x16x32_bf16 v[32:35], v[80:83], v[72:75], v[32:35]
	v_mfma_f32_16x16x32_bf16 v[36:39], v[84:87], v[72:75], v[36:39]
	v_mfma_f32_16x16x32_bf16 v[40:43], v[88:91], v[72:75], v[40:43]
	v_mfma_f32_16x16x32_bf16 v[44:47], v[92:95], v[72:75], v[44:47]
	v_mfma_f32_16x16x32_bf16 v[48:51], v[80:83], v[76:79], v[48:51]
	v_mfma_f32_16x16x32_bf16 v[52:55], v[84:87], v[76:79], v[52:55]
	v_mfma_f32_16x16x32_bf16 v[56:59], v[88:91], v[76:79], v[56:59]
	v_mfma_f32_16x16x32_bf16 v[60:63], v[92:95], v[76:79], v[60:63]
	s_waitcnt lgkmcnt(0)
	s_barrier
	v_mfma_f32_16x16x32_bf16 v[0:3], v[192:195], v[128:131], v[0:3]
	v_mfma_f32_16x16x32_bf16 v[4:7], v[196:199], v[128:131], v[4:7]
	v_mfma_f32_16x16x32_bf16 v[8:11], v[200:203], v[128:131], v[8:11]
	v_mfma_f32_16x16x32_bf16 v[12:15], v[204:207], v[128:131], v[12:15]
	v_mfma_f32_16x16x32_bf16 v[16:19], v[192:195], v[132:135], v[16:19]
	v_mfma_f32_16x16x32_bf16 v[20:23], v[196:199], v[132:135], v[20:23]
	v_mfma_f32_16x16x32_bf16 v[24:27], v[200:203], v[132:135], v[24:27]
	v_mfma_f32_16x16x32_bf16 v[28:31], v[204:207], v[132:135], v[28:31]
	v_mfma_f32_16x16x32_bf16 v[32:35], v[192:195], v[136:139], v[32:35]
	v_mfma_f32_16x16x32_bf16 v[36:39], v[196:199], v[136:139], v[36:39]
	v_mfma_f32_16x16x32_bf16 v[40:43], v[200:203], v[136:139], v[40:43]
	v_mfma_f32_16x16x32_bf16 v[44:47], v[204:207], v[136:139], v[44:47]
	v_mfma_f32_16x16x32_bf16 v[48:51], v[192:195], v[140:143], v[48:51]
	v_mfma_f32_16x16x32_bf16 v[52:55], v[196:199], v[140:143], v[52:55]
	v_mfma_f32_16x16x32_bf16 v[56:59], v[200:203], v[140:143], v[56:59]
	v_mfma_f32_16x16x32_bf16 v[60:63], v[204:207], v[140:143], v[60:63]
	s_waitcnt vmcnt(7)
; DI float ssq_f(u64 v) { return (float)v * (1.f / 1048576.f); }
; DI void gemm_tile(const GemmDesc& d, int m0, int n0, bf16_t* smem, int dry) {
;     ...
;   u32x2 hpre[16];
;   if (d.epi == EPI_RESID) {
; #pragma unroll
;     for (int pass = 0; pass < 16; ++pass) {
;       int m = m0 + pass * 8 + (t >> 5); m = m < M ? m : M - 1;
;       hpre[pass] = *(const u32x2*)(d.hb + (size_t)m * D + d.c_off + n0 + (t & 31) * 4);
;     }
;   } else if (t < 128) {
;     rs_s[t] = rsqrtf(ssq_f(myss) * d.inv_dim + EPS);
;   }
;   if (half) {
; #pragma unroll
;     for (int a = 0; a < 2; ++a)
; #pragma unroll
;       for (int g = 0; g < 4; ++g) {
;         f32x4 o;
; #pragma unroll
;         for (int j = 0; j < 4; ++j) o[j] = acc[a][0][4 * g + j];
;         *(f32x4*)(Ct + (a * 32 + r) * CS + w * 32 + 8 * g + 4 * hh) = o;
;       }
;   } else {
; #pragma unroll
;     for (int a = 0; a < 2; ++a)
; #pragma unroll
;       for (int b = 0; b < 2; ++b)
; #pragma unroll
;         for (int g = 0; g < 4; ++g) {
;           f32x4 o;
; #pragma unroll
;           for (int j = 0; j < 4; ++j) o[j] = acc[a][b][4 * g + j];
;           *(f32x4*)(Ct + (wm * 64 + a * 32 + r) * CS + wn * 64 + b * 32 + 8 * g + 4 * hh) = o;
;         }
;   }
;   __syncthreads();
	v_ashrrev_i32_e32 v98, 5, v150
	v_add_u32_e32 v92, s9, v98
	s_ashr_i32 s5, s4, 31
	s_lshl_b64 s[6:7], s[4:5], 1
	v_add_u32_e32 v70, 16, v92
	v_add_u32_e32 v72, 24, v92
	s_add_u32 s6, s56, s6
	v_lshlrev_b32_e32 v64, 3, v150
	v_min_i32_e32 v66, 0x803f, v92
	v_add_u32_e32 v68, 8, v92
	v_min_i32_e32 v70, 0x803f, v70
	v_min_i32_e32 v72, 0x803f, v72
	s_addc_u32 s7, s57, s7
	v_and_b32_e32 v144, 0xf8, v64
	v_ashrrev_i32_e32 v67, 31, v66
	v_min_i32_e32 v68, 0x803f, v68
	v_ashrrev_i32_e32 v71, 31, v70
	v_ashrrev_i32_e32 v73, 31, v72
	v_lshl_add_u64 v[64:65], s[6:7], 0, v[144:145]
	v_lshlrev_b64 v[66:67], 11, v[66:67]
	v_ashrrev_i32_e32 v69, 31, v68
	v_lshlrev_b64 v[70:71], 11, v[70:71]
	v_lshlrev_b64 v[72:73], 11, v[72:73]
	v_lshl_add_u64 v[66:67], v[64:65], 0, v[66:67]
	v_lshlrev_b64 v[68:69], 11, v[68:69]
	v_lshl_add_u64 v[70:71], v[64:65], 0, v[70:71]
	v_lshl_add_u64 v[72:73], v[64:65], 0, v[72:73]
	v_lshl_add_u64 v[68:69], v[64:65], 0, v[68:69]
	global_load_dwordx2 v[96:97], v[66:67], off
	global_load_dwordx2 v[94:95], v[68:69], off
	global_load_dwordx2 v[90:91], v[70:71], off
	global_load_dwordx2 v[88:89], v[72:73], off
	v_add_u32_e32 v66, 32, v92
	v_add_u32_e32 v70, 48, v92
	v_add_u32_e32 v72, 56, v92
	v_min_i32_e32 v66, 0x803f, v66
	v_add_u32_e32 v68, 40, v92
	v_min_i32_e32 v70, 0x803f, v70
	v_min_i32_e32 v72, 0x803f, v72
	v_ashrrev_i32_e32 v67, 31, v66
	v_min_i32_e32 v68, 0x803f, v68
	v_ashrrev_i32_e32 v71, 31, v70
	v_ashrrev_i32_e32 v73, 31, v72
	v_lshlrev_b64 v[66:67], 11, v[66:67]
	v_ashrrev_i32_e32 v69, 31, v68
	v_lshlrev_b64 v[70:71], 11, v[70:71]
	v_lshlrev_b64 v[72:73], 11, v[72:73]
	v_lshl_add_u64 v[66:67], v[64:65], 0, v[66:67]
	v_lshlrev_b64 v[68:69], 11, v[68:69]
	v_lshl_add_u64 v[70:71], v[64:65], 0, v[70:71]
	v_lshl_add_u64 v[72:73], v[64:65], 0, v[72:73]
	v_lshl_add_u64 v[68:69], v[64:65], 0, v[68:69]
	global_load_dwordx2 v[86:87], v[66:67], off
	global_load_dwordx2 v[84:85], v[68:69], off
	global_load_dwordx2 v[82:83], v[70:71], off
	global_load_dwordx2 v[80:81], v[72:73], off
	v_add_u32_e32 v66, 64, v92
	v_add_u32_e32 v70, 0x50, v92
	v_add_u32_e32 v72, 0x58, v92
	v_min_i32_e32 v66, 0x803f, v66
	v_add_u32_e32 v68, 0x48, v92
	v_min_i32_e32 v70, 0x803f, v70
	v_min_i32_e32 v72, 0x803f, v72
	v_ashrrev_i32_e32 v67, 31, v66
	v_min_i32_e32 v68, 0x803f, v68
	v_ashrrev_i32_e32 v71, 31, v70
	v_ashrrev_i32_e32 v73, 31, v72
	v_lshlrev_b64 v[66:67], 11, v[66:67]
	v_ashrrev_i32_e32 v69, 31, v68
	v_lshlrev_b64 v[70:71], 11, v[70:71]
	v_lshlrev_b64 v[72:73], 11, v[72:73]
	v_lshl_add_u64 v[66:67], v[64:65], 0, v[66:67]
	v_lshlrev_b64 v[68:69], 11, v[68:69]
	v_lshl_add_u64 v[70:71], v[64:65], 0, v[70:71]
	v_lshl_add_u64 v[72:73], v[64:65], 0, v[72:73]
	v_lshl_add_u64 v[68:69], v[64:65], 0, v[68:69]
	global_load_dwordx2 v[78:79], v[66:67], off
	global_load_dwordx2 v[76:77], v[68:69], off
	global_load_dwordx2 v[74:75], v[70:71], off
	s_nop 0
	global_load_dwordx2 v[72:73], v[72:73], off
	v_add_u32_e32 v70, 0x70, v92
	v_min_i32_e32 v70, 0x803f, v70
	v_ashrrev_i32_e32 v71, 31, v70
	v_lshlrev_b64 v[70:71], 11, v[70:71]
	v_add_u32_e32 v66, 0x60, v92
	v_add_u32_e32 v68, 0x68, v92
	s_waitcnt vmcnt(18)
	v_lshl_add_u64 v[100:101], v[64:65], 0, v[70:71]
	v_add_u32_e32 v70, 0x78, v92
	v_min_i32_e32 v66, 0x803f, v66
	v_min_i32_e32 v68, 0x803f, v68
	v_min_i32_e32 v70, 0x803f, v70
	v_ashrrev_i32_e32 v67, 31, v66
	v_ashrrev_i32_e32 v69, 31, v68
	v_ashrrev_i32_e32 v71, 31, v70
	v_lshlrev_b64 v[66:67], 11, v[66:67]
	v_lshlrev_b64 v[68:69], 11, v[68:69]
	v_lshlrev_b64 v[70:71], 11, v[70:71]
	v_lshl_add_u64 v[66:67], v[64:65], 0, v[66:67]
	v_lshl_add_u64 v[68:69], v[64:65], 0, v[68:69]
	v_lshl_add_u64 v[64:65], v[64:65], 0, v[70:71]
	global_load_dwordx2 v[70:71], v[66:67], off
	s_nop 0
	global_load_dwordx2 v[68:69], v[68:69], off
	s_nop 0
	global_load_dwordx2 v[66:67], v[100:101], off
	s_nop 0
	global_load_dwordx2 v[64:65], v[64:65], off
	v_and_b32_e32 v99, 31, v150
	v_lshrrev_b32_e32 v100, 1, v150
	v_lshlrev_b32_e32 v93, 2, v150
	v_and_or_b32 v101, v100, s72, v99
	v_and_b32_e32 v100, 16, v100
	s_movk_i32 s1, 0x100
	v_and_or_b32 v100, v93, s1, v100
	v_mad_u64_u32 v[100:101], s[6:7], v101, s22, v[100:101]
	v_and_b32_e32 v212, 15, v172
	v_lshrrev_b32_e32 v213, 1, v172
	v_and_or_b32 v212, v213, s72, v212
	v_lshlrev_b32_e32 v213, 2, v172
	v_and_b32_e32 v214, 0x30, v172
	v_and_b32_e32 v213, 0x100, v213
	v_or_b32_e32 v213, v213, v214
	v_mad_u32_u24 v100, v212, s22, v213
	ds_write_b128 v100, v[0:3]
	ds_write_b128 v100, v[4:7] offset:64
	ds_write_b128 v100, v[8:11] offset:128
	ds_write_b128 v100, v[12:15] offset:192
	ds_write_b128 v100, v[16:19] offset:8448
	ds_write_b128 v100, v[20:23] offset:8512
	ds_write_b128 v100, v[24:27] offset:8576
	ds_write_b128 v100, v[28:31] offset:8640
	ds_write_b128 v100, v[32:35] offset:16896
	ds_write_b128 v100, v[36:39] offset:16960
	ds_write_b128 v100, v[40:43] offset:17024
	ds_write_b128 v100, v[44:47] offset:17088
	ds_write_b128 v100, v[48:51] offset:25344
	ds_write_b128 v100, v[52:55] offset:25408
	ds_write_b128 v100, v[56:59] offset:25472
	ds_write_b128 v100, v[60:63] offset:25536
	v_lshl_or_b32 v0, v99, 2, s4
	v_lshlrev_b32_e32 v2, 4, v99
	v_cmp_gt_i32_e64 s[4:5], s23, v92
	v_mov_b32_e32 v4, 0
	v_ashrrev_i32_e32 v93, 31, v92
	v_ashrrev_i32_e32 v1, 31, v0
	s_waitcnt lgkmcnt(0)
	s_barrier
	s_and_saveexec_b64 s[6:7], s[4:5]
	s_cbranch_execz .LBB0_923
	v_mad_u64_u32 v[4:5], s[10:11], v98, s22, v[2:3]
	ds_read_b128 v[4:7], v4
	s_waitcnt vmcnt(15)
	v_lshlrev_b32_e32 v8, 16, v96
	v_and_b32_e32 v9, 0xffff0000, v96
	v_and_b32_e32 v11, 0xffff0000, v97
	v_lshlrev_b32_e32 v10, 16, v97
	s_waitcnt lgkmcnt(0)
	v_pk_add_f32 v[8:9], v[4:5], v[8:9]
	v_pk_add_f32 v[6:7], v[6:7], v[10:11]
	v_pk_mul_f32 v[4:5], v[8:9], v[8:9]
	v_pk_mul_f32 v[10:11], v[6:7], v[6:7]
	v_add_f32_e32 v3, v4, v5
	v_cvt_pk_bf16_f32 v8, v8, v9
	v_cvt_pk_bf16_f32 v9, v6, v7
	v_lshlrev_b64 v[6:7], 11, v[92:93]
	v_add_f32_e32 v3, v10, v3
	v_lshl_add_u64 v[6:7], s[56:57], 0, v[6:7]
	v_add_f32_e32 v4, v11, v3
	v_lshl_add_u64 v[6:7], v[0:1], 1, v[6:7]
	global_store_dwordx2 v[6:7], v[8:9], off
